# xattn K-staging copies de-serialised; one more of the unit's stores rides into phase 4 of the next unit's peeled first trip
# baseline (speedup 1.0000x reference)
.Lp2_next:
	v_cvt_pk_bf16_f32 v120, v120, v121
	v_cvt_pk_bf16_f32 v121, v122, v123
	v_cvt_pk_bf16_f32 v122, v116, v117
	v_cvt_pk_bf16_f32 v123, v118, v119
	v_cvt_pk_bf16_f32 v104, v104, v105
	v_cvt_pk_bf16_f32 v105, v106, v107
	v_cvt_pk_bf16_f32 v106, v100, v101
	v_cvt_pk_bf16_f32 v107, v102, v103
	v_cvt_pk_bf16_f32 v88, v88, v89
	v_cvt_pk_bf16_f32 v89, v90, v91
	v_cvt_pk_bf16_f32 v90, v84, v85
	v_cvt_pk_bf16_f32 v91, v86, v87
	v_cvt_pk_bf16_f32 v76, v76, v77
	v_cvt_pk_bf16_f32 v77, v78, v79
	v_cvt_pk_bf16_f32 v78, v72, v73
	v_cvt_pk_bf16_f32 v79, v74, v75
	v_cvt_pk_bf16_f32 v140, v68, v69
	v_cvt_pk_bf16_f32 v141, v70, v71
	v_cvt_pk_bf16_f32 v142, v64, v65
	v_cvt_pk_bf16_f32 v143, v66, v67
	v_cvt_pk_bf16_f32 v60, v60, v61
	v_cvt_pk_bf16_f32 v61, v62, v63
	v_cvt_pk_bf16_f32 v62, v56, v57
	v_cvt_pk_bf16_f32 v63, v58, v59
	v_cvt_pk_bf16_f32 v52, v52, v53
	v_cvt_pk_bf16_f32 v53, v54, v55
	v_cvt_pk_bf16_f32 v54, v48, v49
	v_cvt_pk_bf16_f32 v55, v50, v51
	v_cvt_pk_bf16_f32 v44, v44, v45
	v_cvt_pk_bf16_f32 v45, v46, v47
	v_cvt_pk_bf16_f32 v46, v40, v41
	v_cvt_pk_bf16_f32 v47, v42, v43
	v_cvt_pk_bf16_f32 v36, v36, v37
	v_cvt_pk_bf16_f32 v37, v38, v39
	v_cvt_pk_bf16_f32 v38, v32, v33
	v_cvt_pk_bf16_f32 v39, v34, v35
	v_cvt_pk_bf16_f32 v28, v28, v29
	v_cvt_pk_bf16_f32 v29, v30, v31
	v_cvt_pk_bf16_f32 v30, v24, v25
	v_cvt_pk_bf16_f32 v31, v26, v27
	v_cvt_pk_bf16_f32 v20, v20, v21
	v_cvt_pk_bf16_f32 v21, v22, v23
	v_cvt_pk_bf16_f32 v22, v16, v17
	v_cvt_pk_bf16_f32 v23, v18, v19
	v_cvt_pk_bf16_f32 v144, v12, v13
	v_cvt_pk_bf16_f32 v145, v14, v15
	v_cvt_pk_bf16_f32 v146, v8, v9
	v_cvt_pk_bf16_f32 v147, v10, v11
	v_cvt_pk_bf16_f32 v148, v4, v5
	v_cvt_pk_bf16_f32 v149, v6, v7
	v_cvt_pk_bf16_f32 v150, v0, v1
	v_cvt_pk_bf16_f32 v151, v2, v3
	s_mov_b32 s42, s40
	s_mov_b32 s43, s41
	s_mov_b64 s[20:21], s[8:9]
	s_mov_b64 s[18:19], s[10:11]
	s_add_u32 s22, s20, 0x80
	s_addc_u32 s23, s21, 0
	v_lshl_add_u64 v[164:165], s[22:23], 0, v[156:157]
	s_add_i32 m0, s29, 0xc000
	s_nop 0
	global_load_lds_dwordx4 v[164:165], off
	v_lshl_add_u64 v[164:165], s[22:23], 0, v[154:155]
	s_add_i32 m0, s29, 0xe000
	s_nop 0
	global_load_lds_dwordx4 v[164:165], off
	s_add_u32 s78, s98, 0x6000
	s_addc_u32 s79, s99, 0
	global_store_dwordx4 v138, v[76:79], s[78:79] nt
	s_add_u32 s78, s98, 0x0
	s_addc_u32 s79, s99, 0
	global_store_dwordx4 v138, v[120:123], s[78:79] offset:256 nt
	s_add_u32 s78, s98, 0x2000
	s_addc_u32 s79, s99, 0
	global_store_dwordx4 v138, v[104:107], s[78:79] offset:256 nt
	s_add_u32 s78, s98, 0x10000
	s_addc_u32 s79, s99, 0
	global_store_dwordx4 v138, v[60:63], s[78:79] nt
	s_add_u32 s78, s98, 0x12000
	s_addc_u32 s79, s99, 0
	global_store_dwordx4 v138, v[44:47], s[78:79] nt
	s_add_u32 s78, s98, 0x10000
	s_addc_u32 s79, s99, 0
	global_store_dwordx4 v138, v[52:55], s[78:79] offset:256 nt
	s_add_i32 s39, s39, 1
	s_mul_i32 s6, s3, s39
	s_mul_hi_u32 s7, s2, s39
	s_add_i32 s7, s7, s6
	s_mul_i32 s6, s2, s39
	s_add_u32 s10, s6, s64
	s_addc_u32 s11, s7, s65
	v_mov_b64_e32 v[160:161], 0xc40
	v_cmp_lt_i64_e64 s[8:9], s[10:11], v[160:161]
	v_mov_b64_e32 v[160:161], 0xc3f
	v_cmp_gt_i64_e64 s[6:7], s[10:11], v[160:161]
	s_and_b64 vcc, exec, s[6:7]
	s_cbranch_vccnz .Lp2_u217
	s_ashr_i32 s11, s10, 31
	s_lshr_b32 s11, s11, 29
	s_add_i32 s11, s10, s11
	s_ashr_i32 s22, s11, 3
	s_and_b32 s11, s11, -8
	s_sub_i32 s10, s10, s11
	s_cmp_lt_i32 s10, 0
	s_cselect_b32 s11, s69, 0x188
	s_mul_i32 s10, s10, s11
	s_add_i32 s10, s10, s22
	s_mul_hi_i32 s11, s10, 0x5397829d
	s_lshr_b32 s22, s11, 31
	s_ashr_i32 s11, s11, 6
	s_add_i32 s11, s11, s22
	s_lshl_b32 s22, s11, 2
	s_sub_i32 s23, 64, s22
	s_min_i32 s23, s23, 4
	s_abs_i32 s40, s23
	v_cvt_f32_u32_e32 v160, s40
	s_sub_i32 s44, 0, s40
	s_mulk_i32 s11, 0xc4
	s_sub_i32 s10, s10, s11
	v_rcp_iflag_f32_e32 v160, v160
	s_abs_i32 s11, s10
	s_xor_b32 s41, s10, s23
	s_ashr_i32 s41, s41, 31
	v_mul_f32_e32 v160, 0x4f7ffffe, v160
	v_cvt_u32_f32_e32 v160, v160
	s_nop 0
	v_readfirstlane_b32 s45, v160
	s_mul_i32 s44, s44, s45
	s_mul_hi_u32 s44, s45, s44
	s_add_i32 s45, s45, s44
	s_mul_hi_u32 s44, s11, s45
	s_mul_i32 s45, s44, s40
	s_sub_i32 s11, s11, s45
	s_add_i32 s46, s44, 1
	s_sub_i32 s45, s11, s40
	s_cmp_ge_u32 s11, s40
	s_cselect_b32 s44, s46, s44
	s_cselect_b32 s11, s45, s11
	s_add_i32 s45, s44, 1
	s_cmp_ge_u32 s11, s40
	s_cselect_b32 s11, s45, s44
	s_xor_b32 s11, s11, s41
	s_sub_i32 s40, s11, s41
	s_mul_i32 s11, s40, s23
	s_sub_i32 s10, s10, s11
	s_add_i32 s41, s22, s10

.Lp2_u221:
	s_add_u32 s44, s18, 0x100
	s_addc_u32 s45, s19, 0
	s_add_u32 s18, s20, 0x80
	s_addc_u32 s19, s21, 0
	s_mov_b32 s20, 0
	s_add_i32 s46, s20, 2
	s_add_u32 s22, s18, 0x80
	s_addc_u32 s21, s19, 0
	s_add_i32 s47, 0, 0x10000
	v_add_u32_e32 v164, s47, v158
	ds_read_b128 v[160:163], v164
	ds_read_b128 v[176:179], v164 offset:1024
	ds_read_b128 v[180:183], v164 offset:2048
	ds_read_b128 v[184:187], v164 offset:3072
	s_cmp_eq_u32 s38, s20
	s_cselect_b32 s20, s8, s22
	s_cselect_b32 s21, s9, s21
	s_cselect_b32 s23, s11, s45
	s_cselect_b32 s22, s10, s44
	ds_read_b128 v[188:191], v159
	ds_read_b128 v[192:195], v159 offset:1024
	ds_read_b128 v[196:199], v159 offset:2048
	ds_read_b128 v[200:203], v159 offset:3072
	ds_read_b128 v[204:207], v159 offset:4096
	ds_read_b128 v[218:221], v159 offset:5120
	ds_read_b128 v[224:227], v159 offset:6144
	ds_read_b128 v[228:231], v159 offset:7168
	s_add_u32 s78, s98, 0x4000
	s_addc_u32 s79, s99, 0
	global_store_dwordx4 v138, v[88:91], s[78:79] offset:256 nt
	s_waitcnt lgkmcnt(8)
	s_barrier
	s_waitcnt lgkmcnt(0)
	s_setprio 1
	s_waitcnt lgkmcnt(0)
	v_mfma_f32_16x16x32_bf16 v[124:127], v[160:163], v[188:191], 0
	v_mfma_f32_16x16x32_bf16 v[128:131], v[180:183], v[188:191], 0
	v_mfma_f32_16x16x32_bf16 v[112:115], v[160:163], v[196:199], 0
	v_mfma_f32_16x16x32_bf16 v[108:111], v[180:183], v[196:199], 0
	v_mfma_f32_16x16x32_bf16 v[96:99], v[160:163], v[204:207], 0
	v_mfma_f32_16x16x32_bf16 v[92:95], v[180:183], v[204:207], 0
	v_mfma_f32_16x16x32_bf16 v[76:79], v[160:163], v[224:227], 0
	v_mfma_f32_16x16x32_bf16 v[72:75], v[180:183], v[224:227], 0
	v_mfma_f32_16x16x32_bf16 v[124:127], v[176:179], v[192:195], v[124:127]
	v_mfma_f32_16x16x32_bf16 v[128:131], v[184:187], v[192:195], v[128:131]
	v_mfma_f32_16x16x32_bf16 v[112:115], v[176:179], v[200:203], v[112:115]
	v_mfma_f32_16x16x32_bf16 v[108:111], v[184:187], v[200:203], v[108:111]
	v_mfma_f32_16x16x32_bf16 v[96:99], v[176:179], v[218:221], v[96:99]
	v_mfma_f32_16x16x32_bf16 v[92:95], v[184:187], v[218:221], v[92:95]
	v_mfma_f32_16x16x32_bf16 v[76:79], v[176:179], v[228:231], v[76:79]
	v_mfma_f32_16x16x32_bf16 v[72:75], v[184:187], v[228:231], v[72:75]
	s_setprio 0
	s_barrier
	s_add_i32 s48, 0, 0x14000
	v_add_u32_e32 v164, s48, v158
	s_add_i32 s47, s47, s28
	ds_read_b128 v[232:235], v164
	ds_read_b128 v[236:239], v164 offset:1024
	ds_read_b128 v[240:243], v164 offset:2048
	ds_read_b128 v[244:247], v164 offset:3072
	v_lshl_add_u64 v[164:165], s[22:23], 0, v[166:167]
	s_mov_b32 m0, s47
	v_lshl_add_u64 v[248:249], s[22:23], 0, v[132:133]
	global_load_lds_dwordx4 v[164:165], off
	s_add_i32 m0, s47, 0x2000
	s_nop 0
	global_load_lds_dwordx4 v[248:249], off
	s_add_u32 s78, s98, 0x14000
	s_addc_u32 s79, s99, 0
	global_store_dwordx4 v138, v[28:31], s[78:79] nt
	s_barrier
	s_waitcnt lgkmcnt(0)
	s_setprio 1
	s_waitcnt lgkmcnt(0)
	v_mfma_f32_16x16x32_bf16 v[120:123], v[232:235], v[188:191], 0
	v_mfma_f32_16x16x32_bf16 v[116:119], v[240:243], v[188:191], 0
	v_mfma_f32_16x16x32_bf16 v[104:107], v[232:235], v[196:199], 0
	v_mfma_f32_16x16x32_bf16 v[100:103], v[240:243], v[196:199], 0
	v_mfma_f32_16x16x32_bf16 v[88:91], v[232:235], v[204:207], 0
	v_mfma_f32_16x16x32_bf16 v[84:87], v[240:243], v[204:207], 0
	v_mfma_f32_16x16x32_bf16 v[68:71], v[232:235], v[224:227], 0
	v_mfma_f32_16x16x32_bf16 v[64:67], v[240:243], v[224:227], 0
	v_mfma_f32_16x16x32_bf16 v[120:123], v[236:239], v[192:195], v[120:123]
	v_mfma_f32_16x16x32_bf16 v[116:119], v[244:247], v[192:195], v[116:119]
	v_mfma_f32_16x16x32_bf16 v[104:107], v[236:239], v[200:203], v[104:107]
	v_mfma_f32_16x16x32_bf16 v[100:103], v[244:247], v[200:203], v[100:103]
	v_mfma_f32_16x16x32_bf16 v[88:91], v[236:239], v[218:221], v[88:91]
	v_mfma_f32_16x16x32_bf16 v[84:87], v[244:247], v[218:221], v[84:87]
	v_mfma_f32_16x16x32_bf16 v[68:71], v[236:239], v[228:231], v[68:71]
	v_mfma_f32_16x16x32_bf16 v[64:67], v[244:247], v[228:231], v[64:67]
	s_setprio 0
	s_mov_b32 m0, s29
	v_lshl_add_u64 v[250:251], s[20:21], 0, v[136:137]
	s_barrier
	ds_read_b128 v[188:191], v159 offset:16384
	ds_read_b128 v[192:195], v159 offset:17408
	ds_read_b128 v[196:199], v159 offset:18432
	ds_read_b128 v[200:203], v159 offset:19456
	ds_read_b128 v[204:207], v159 offset:20480
	ds_read_b128 v[218:221], v159 offset:21504
	ds_read_b128 v[224:227], v159 offset:22528
	ds_read_b128 v[228:231], v159 offset:23552
	global_load_lds_dwordx4 v[250:251], off
	v_lshl_add_u64 v[210:211], s[20:21], 0, v[134:135]
	s_mov_b32 m0, s30
	s_nop 0
	global_load_lds_dwordx4 v[210:211], off
	s_add_u32 s78, s98, 0x14000
	s_addc_u32 s79, s99, 0
	global_store_dwordx4 v138, v[20:23], s[78:79] offset:256 nt
	s_barrier
	s_waitcnt lgkmcnt(0)
	s_setprio 1
	s_waitcnt lgkmcnt(0)
	v_mfma_f32_16x16x32_bf16 v[60:63], v[160:163], v[188:191], 0
	v_mfma_f32_16x16x32_bf16 v[56:59], v[180:183], v[188:191], 0
	v_mfma_f32_16x16x32_bf16 v[44:47], v[160:163], v[196:199], 0
	v_mfma_f32_16x16x32_bf16 v[40:43], v[180:183], v[196:199], 0
	v_mfma_f32_16x16x32_bf16 v[28:31], v[160:163], v[204:207], 0
	v_mfma_f32_16x16x32_bf16 v[24:27], v[180:183], v[204:207], 0
	v_mfma_f32_16x16x32_bf16 v[12:15], v[160:163], v[224:227], 0
	v_mfma_f32_16x16x32_bf16 v[8:11], v[180:183], v[224:227], 0
	v_mfma_f32_16x16x32_bf16 v[60:63], v[176:179], v[192:195], v[60:63]
	v_mfma_f32_16x16x32_bf16 v[56:59], v[184:187], v[192:195], v[56:59]
	v_mfma_f32_16x16x32_bf16 v[44:47], v[176:179], v[200:203], v[44:47]
	v_mfma_f32_16x16x32_bf16 v[40:43], v[184:187], v[200:203], v[40:43]
	v_mfma_f32_16x16x32_bf16 v[28:31], v[176:179], v[218:221], v[28:31]
	v_mfma_f32_16x16x32_bf16 v[24:27], v[184:187], v[218:221], v[24:27]
	v_mfma_f32_16x16x32_bf16 v[12:15], v[176:179], v[228:231], v[12:15]
	v_mfma_f32_16x16x32_bf16 v[8:11], v[184:187], v[228:231], v[8:11]
	s_setprio 0
	s_barrier
	s_add_u32 s22, s22, s12
	s_addc_u32 s23, s23, s13
	s_add_i32 s47, s48, s28
	v_lshl_add_u64 v[170:171], s[22:23], 0, v[166:167]
	s_mov_b32 m0, s47
	v_lshl_add_u64 v[172:173], s[22:23], 0, v[132:133]
	global_load_lds_dwordx4 v[170:171], off
	s_add_i32 m0, s47, 0x2000
	s_nop 0
	global_load_lds_dwordx4 v[172:173], off
	s_add_u32 s78, s98, 0x12000
	s_addc_u32 s79, s99, 0
	global_store_dwordx4 v138, v[36:39], s[78:79] offset:256 nt
	s_waitcnt vmcnt(16)
	s_barrier
	s_setprio 1
	v_mfma_f32_16x16x32_bf16 v[52:55], v[232:235], v[188:191], 0
	v_mfma_f32_16x16x32_bf16 v[48:51], v[240:243], v[188:191], 0
	v_mfma_f32_16x16x32_bf16 v[36:39], v[232:235], v[196:199], 0
	v_mfma_f32_16x16x32_bf16 v[32:35], v[240:243], v[196:199], 0
	v_mfma_f32_16x16x32_bf16 v[20:23], v[232:235], v[204:207], 0
	v_mfma_f32_16x16x32_bf16 v[16:19], v[240:243], v[204:207], 0
	v_mfma_f32_16x16x32_bf16 v[4:7], v[232:235], v[224:227], 0
	v_mfma_f32_16x16x32_bf16 v[0:3], v[240:243], v[224:227], 0
	v_mfma_f32_16x16x32_bf16 v[52:55], v[236:239], v[192:195], v[52:55]
	v_mfma_f32_16x16x32_bf16 v[48:51], v[244:247], v[192:195], v[48:51]
	v_mfma_f32_16x16x32_bf16 v[36:39], v[236:239], v[200:203], v[36:39]
	v_mfma_f32_16x16x32_bf16 v[32:35], v[244:247], v[200:203], v[32:35]
	v_mfma_f32_16x16x32_bf16 v[20:23], v[236:239], v[218:221], v[20:23]
	v_mfma_f32_16x16x32_bf16 v[16:19], v[244:247], v[218:221], v[16:19]
	v_mfma_f32_16x16x32_bf16 v[4:7], v[236:239], v[228:231], v[4:7]
	v_mfma_f32_16x16x32_bf16 v[0:3], v[244:247], v[228:231], v[0:3]
	s_setprio 0
	s_add_i32 s22, 0, 0x18000
	v_add_u32_e32 v169, s22, v158
	s_barrier
	ds_read_b128 v[160:163], v169
	ds_read_b128 v[176:179], v169 offset:1024
	ds_read_b128 v[180:183], v169 offset:2048
	ds_read_b128 v[184:187], v169 offset:3072
	s_add_u32 s20, s20, s12
	s_addc_u32 s21, s21, s13
	s_mov_b32 m0, s31
	v_lshl_add_u64 v[232:233], s[20:21], 0, v[136:137]
	ds_read_b128 v[188:191], v159 offset:32768
	ds_read_b128 v[192:195], v159 offset:33792
	ds_read_b128 v[196:199], v159 offset:34816
	ds_read_b128 v[200:203], v159 offset:35840
	ds_read_b128 v[204:207], v159 offset:36864
	ds_read_b128 v[218:221], v159 offset:37888
	ds_read_b128 v[224:227], v159 offset:38912
	ds_read_b128 v[228:231], v159 offset:39936
	global_load_lds_dwordx4 v[232:233], off
	v_lshl_add_u64 v[232:233], s[20:21], 0, v[134:135]
	s_mov_b32 m0, s34
	s_nop 0
	global_load_lds_dwordx4 v[232:233], off
	s_add_u32 s78, s98, 0x6000
	s_addc_u32 s79, s99, 0
	global_store_dwordx4 v138, v[140:143], s[78:79] offset:256 nt
	s_waitcnt lgkmcnt(8)
	s_barrier
	s_waitcnt lgkmcnt(0)
	s_setprio 1
	s_waitcnt lgkmcnt(0)
	v_mfma_f32_16x16x32_bf16 v[124:127], v[160:163], v[188:191], v[124:127]
	v_mfma_f32_16x16x32_bf16 v[128:131], v[180:183], v[188:191], v[128:131]
	v_mfma_f32_16x16x32_bf16 v[112:115], v[160:163], v[196:199], v[112:115]
	v_mfma_f32_16x16x32_bf16 v[108:111], v[180:183], v[196:199], v[108:111]
	v_mfma_f32_16x16x32_bf16 v[96:99], v[160:163], v[204:207], v[96:99]
	v_mfma_f32_16x16x32_bf16 v[92:95], v[180:183], v[204:207], v[92:95]
	v_mfma_f32_16x16x32_bf16 v[76:79], v[160:163], v[224:227], v[76:79]
	v_mfma_f32_16x16x32_bf16 v[72:75], v[180:183], v[224:227], v[72:75]
	v_mfma_f32_16x16x32_bf16 v[124:127], v[176:179], v[192:195], v[124:127]
	v_mfma_f32_16x16x32_bf16 v[128:131], v[184:187], v[192:195], v[128:131]
	v_mfma_f32_16x16x32_bf16 v[112:115], v[176:179], v[200:203], v[112:115]
	v_mfma_f32_16x16x32_bf16 v[108:111], v[184:187], v[200:203], v[108:111]
	v_mfma_f32_16x16x32_bf16 v[96:99], v[176:179], v[218:221], v[96:99]
	v_mfma_f32_16x16x32_bf16 v[92:95], v[184:187], v[218:221], v[92:95]
	v_mfma_f32_16x16x32_bf16 v[76:79], v[176:179], v[228:231], v[76:79]
	v_mfma_f32_16x16x32_bf16 v[72:75], v[184:187], v[228:231], v[72:75]
	s_setprio 0
	s_barrier
	s_add_i32 s20, 0, 0x1c000
	s_add_i32 s21, s22, s28
	v_add_u32_e32 v169, s20, v158
	v_lshl_add_u64 v[164:165], v[164:165], 0, s[88:89]
	s_mov_b32 m0, s21
	ds_read_b128 v[232:235], v169
	ds_read_b128 v[236:239], v169 offset:1024
	ds_read_b128 v[240:243], v169 offset:2048
	ds_read_b128 v[244:247], v169 offset:3072
	global_load_lds_dwordx4 v[164:165], off
	v_lshl_add_u64 v[164:165], v[248:249], 0, s[88:89]
	s_add_i32 m0, s21, 0x2000
	s_nop 0
	global_load_lds_dwordx4 v[164:165], off
	s_add_u32 s78, s98, 0x16000
	s_addc_u32 s79, s99, 0
	global_store_dwordx4 v138, v[144:147], s[78:79] nt
	s_barrier
	s_waitcnt lgkmcnt(0)
	s_setprio 1
	s_waitcnt lgkmcnt(0)
	v_mfma_f32_16x16x32_bf16 v[120:123], v[232:235], v[188:191], v[120:123]
	v_mfma_f32_16x16x32_bf16 v[116:119], v[240:243], v[188:191], v[116:119]
	v_mfma_f32_16x16x32_bf16 v[104:107], v[232:235], v[196:199], v[104:107]
	v_mfma_f32_16x16x32_bf16 v[100:103], v[240:243], v[196:199], v[100:103]
	v_mfma_f32_16x16x32_bf16 v[88:91], v[232:235], v[204:207], v[88:91]
	v_mfma_f32_16x16x32_bf16 v[84:87], v[240:243], v[204:207], v[84:87]
	v_mfma_f32_16x16x32_bf16 v[68:71], v[232:235], v[224:227], v[68:71]
	v_mfma_f32_16x16x32_bf16 v[64:67], v[240:243], v[224:227], v[64:67]
	v_mfma_f32_16x16x32_bf16 v[120:123], v[236:239], v[192:195], v[120:123]
	v_mfma_f32_16x16x32_bf16 v[116:119], v[244:247], v[192:195], v[116:119]
	v_mfma_f32_16x16x32_bf16 v[104:107], v[236:239], v[200:203], v[104:107]
	v_mfma_f32_16x16x32_bf16 v[100:103], v[244:247], v[200:203], v[100:103]
	v_mfma_f32_16x16x32_bf16 v[88:91], v[236:239], v[218:221], v[88:91]
	v_mfma_f32_16x16x32_bf16 v[84:87], v[244:247], v[218:221], v[84:87]
	v_mfma_f32_16x16x32_bf16 v[68:71], v[236:239], v[228:231], v[68:71]
	v_mfma_f32_16x16x32_bf16 v[64:67], v[244:247], v[228:231], v[64:67]
	s_setprio 0
	s_mov_b32 m0, s36
	v_lshl_add_u64 v[164:165], v[250:251], 0, s[88:89]
	s_barrier
	ds_read_b128 v[188:191], v159 offset:49152
	ds_read_b128 v[192:195], v159 offset:50176
	ds_read_b128 v[196:199], v159 offset:51200
	ds_read_b128 v[200:203], v159 offset:52224
	ds_read_b128 v[204:207], v159 offset:53248
	ds_read_b128 v[218:221], v159 offset:54272
	ds_read_b128 v[224:227], v159 offset:55296
	ds_read_b128 v[228:231], v159 offset:56320
	global_load_lds_dwordx4 v[164:165], off
	v_lshl_add_u64 v[164:165], v[210:211], 0, s[88:89]
	s_mov_b32 m0, s37
	s_nop 0
	global_load_lds_dwordx4 v[164:165], off
	s_add_u32 s78, s98, 0x16000
	s_addc_u32 s79, s99, 0
	global_store_dwordx4 v138, v[148:151], s[78:79] offset:256 nt
	s_barrier
	s_waitcnt lgkmcnt(0)
	s_setprio 1
	s_waitcnt lgkmcnt(0)
	v_mfma_f32_16x16x32_bf16 v[60:63], v[160:163], v[188:191], v[60:63]
	v_mfma_f32_16x16x32_bf16 v[56:59], v[180:183], v[188:191], v[56:59]
	v_mfma_f32_16x16x32_bf16 v[44:47], v[160:163], v[196:199], v[44:47]
	v_mfma_f32_16x16x32_bf16 v[40:43], v[180:183], v[196:199], v[40:43]
	v_mfma_f32_16x16x32_bf16 v[28:31], v[160:163], v[204:207], v[28:31]
	v_mfma_f32_16x16x32_bf16 v[24:27], v[180:183], v[204:207], v[24:27]
	v_mfma_f32_16x16x32_bf16 v[12:15], v[160:163], v[224:227], v[12:15]
	v_mfma_f32_16x16x32_bf16 v[8:11], v[180:183], v[224:227], v[8:11]
	v_mfma_f32_16x16x32_bf16 v[60:63], v[176:179], v[192:195], v[60:63]
	v_mfma_f32_16x16x32_bf16 v[56:59], v[184:187], v[192:195], v[56:59]
	v_mfma_f32_16x16x32_bf16 v[44:47], v[176:179], v[200:203], v[44:47]
	v_mfma_f32_16x16x32_bf16 v[40:43], v[184:187], v[200:203], v[40:43]
	v_mfma_f32_16x16x32_bf16 v[28:31], v[176:179], v[218:221], v[28:31]
	v_mfma_f32_16x16x32_bf16 v[24:27], v[184:187], v[218:221], v[24:27]
	v_mfma_f32_16x16x32_bf16 v[12:15], v[176:179], v[228:231], v[12:15]
	v_mfma_f32_16x16x32_bf16 v[8:11], v[184:187], v[228:231], v[8:11]
	s_setprio 0
	s_barrier
	s_add_i32 s20, s20, s28
	v_lshl_add_u64 v[160:161], v[170:171], 0, s[88:89]
	s_mov_b32 m0, s20
	s_nop 0
	global_load_lds_dwordx4 v[160:161], off
	v_lshl_add_u64 v[160:161], v[172:173], 0, s[88:89]
	s_add_i32 m0, s20, 0x2000
	s_nop 0
	global_load_lds_dwordx4 v[160:161], off
	s_waitcnt vmcnt(9)
	s_barrier
	s_setprio 1
	v_mfma_f32_16x16x32_bf16 v[52:55], v[232:235], v[188:191], v[52:55]
	v_mfma_f32_16x16x32_bf16 v[48:51], v[240:243], v[188:191], v[48:51]
	v_mfma_f32_16x16x32_bf16 v[36:39], v[232:235], v[196:199], v[36:39]
	v_mfma_f32_16x16x32_bf16 v[32:35], v[240:243], v[196:199], v[32:35]
	v_mfma_f32_16x16x32_bf16 v[20:23], v[232:235], v[204:207], v[20:23]
	v_mfma_f32_16x16x32_bf16 v[16:19], v[240:243], v[204:207], v[16:19]
	v_mfma_f32_16x16x32_bf16 v[4:7], v[232:235], v[224:227], v[4:7]
	v_mfma_f32_16x16x32_bf16 v[0:3], v[240:243], v[224:227], v[0:3]
	v_mfma_f32_16x16x32_bf16 v[52:55], v[236:239], v[192:195], v[52:55]
	v_mfma_f32_16x16x32_bf16 v[48:51], v[244:247], v[192:195], v[48:51]
	v_mfma_f32_16x16x32_bf16 v[36:39], v[236:239], v[200:203], v[36:39]
	v_mfma_f32_16x16x32_bf16 v[32:35], v[244:247], v[200:203], v[32:35]
	v_mfma_f32_16x16x32_bf16 v[20:23], v[236:239], v[218:221], v[20:23]
	v_mfma_f32_16x16x32_bf16 v[16:19], v[244:247], v[218:221], v[16:19]
	v_mfma_f32_16x16x32_bf16 v[4:7], v[236:239], v[228:231], v[4:7]
	v_mfma_f32_16x16x32_bf16 v[0:3], v[244:247], v[228:231], v[0:3]
	s_setprio 0
	s_add_u32 s44, s44, 0x100
	s_addc_u32 s45, s45, 0
	s_add_u32 s18, s18, 0x100
	s_addc_u32 s19, s19, 0
	s_mov_b32 s20, s46
	s_barrier
	s_branch .LBB0_223

.LBB0_305:
	s_mov_b64 s[6:7], s[62:63]
	global_load_dwordx2 v[64:65], v167, s[6:7] offset:192
	s_lshl_b32 s96, s37, 1
	v_mov_b32_e32 v4, v208
	s_mov_b64 s[8:9], 0x4b00000
	s_ashr_i32 s6, s5, 5
	v_lshlrev_b32_e32 v5, 4, v4
	s_lshl_b32 s7, s6, 8
	v_and_b32_e32 v166, 0x70, v5
	v_ashrrev_i32_e32 v5, 3, v4
	v_add_u32_e32 v6, s7, v5
	v_ashrrev_i32_e32 v7, 31, v6
	v_lshlrev_b64 v[6:7], 12, v[6:7]
	v_add_u32_e32 v10, 0, v166
	v_mad_u64_u32 v[12:13], s[10:11], v5, s94, v[10:11]
	v_add_u32_e32 v11, 0x200, v4
	v_ashrrev_i32_e32 v5, 3, v11
	v_add_u32_e32 v14, 0x400, v4
	v_and_b32_e32 v88, 31, v4
	s_lshl_b32 s6, s6, 11
	v_bfe_u32 v37, v4, 5, 1
	v_mov_b32_e32 v38, s92
	v_lshl_add_u32 v89, v37, 4, 0
	s_waitcnt vmcnt(0)
	v_lshl_add_u64 v[0:1], v[64:65], 0, s[96:97]
	v_lshl_add_u64 v[0:1], v[0:1], 0, s[8:9]
	s_lshl_b32 s8, s5, 3
	s_and_b32 s8, s8, 0xc0
	s_lshl_b32 s96, s8, 1
	v_lshl_add_u64 v[2:3], v[0:1], 0, s[96:97]
	v_lshl_add_u64 v[2:3], v[2:3], 0, v[166:167]
	v_lshl_add_u64 v[6:7], v[2:3], 0, v[6:7]
	s_mov_b32 s9, 0
	s_mov_b64 s[10:11], 0x40000
	v_mov_b32_e32 v3, v12
	global_load_dwordx4 v[24:27], v[6:7], off
	v_lshl_add_u64 v[6:7], v[6:7], 0, s[10:11]
	global_load_dwordx4 v[28:31], v[6:7], off
	v_lshl_add_u64 v[6:7], v[6:7], 0, s[10:11]
	global_load_dwordx4 v[32:35], v[6:7], off
	v_lshl_add_u64 v[6:7], v[6:7], 0, s[10:11]
	global_load_dwordx4 v[40:43], v[6:7], off
	v_add_u32_e32 v12, 0x600, v4
	v_ashrrev_i32_e32 v5, 5, v4
	s_waitcnt vmcnt(0)
	ds_write_b128 v3, v[24:27]
	ds_write_b128 v3, v[28:31] offset:9216
	ds_write_b128 v3, v[32:35] offset:18432
	ds_write_b128 v3, v[40:43] offset:27648
	v_add_u32_e32 v2, s7, v5
	v_ashrrev_i32_e32 v3, 31, v2
	v_lshlrev_b64 v[2:3], 12, v[2:3]
	v_lshl_add_u64 v[2:3], v[0:1], 0, v[2:3]
	v_lshlrev_b32_e32 v6, 2, v4
	v_lshl_add_u64 v[2:3], v[2:3], 0, s[96:97]
	v_and_b32_e32 v166, 0x7c, v6
	v_lshl_add_u64 v[2:3], v[2:3], 0, v[166:167]
	v_ashrrev_i32_e32 v7, 5, v11
	global_load_dword v6, v[2:3], off offset:512
	v_add_u32_e32 v2, s7, v7
	v_ashrrev_i32_e32 v3, 31, v2
	v_lshlrev_b64 v[2:3], 12, v[2:3]
	v_lshl_add_u64 v[2:3], v[0:1], 0, v[2:3]
	v_lshl_add_u64 v[2:3], v[2:3], 0, s[96:97]
	v_lshl_add_u64 v[2:3], v[2:3], 0, v[166:167]
	v_ashrrev_i32_e32 v9, 5, v14
	global_load_dword v8, v[2:3], off offset:512
	v_add_u32_e32 v2, s7, v9
	v_ashrrev_i32_e32 v3, 31, v2
	v_lshlrev_b64 v[2:3], 12, v[2:3]
	v_lshl_add_u64 v[2:3], v[0:1], 0, v[2:3]
	v_lshl_add_u64 v[2:3], v[2:3], 0, s[96:97]
	v_lshl_add_u64 v[2:3], v[2:3], 0, v[166:167]
	v_ashrrev_i32_e32 v11, 5, v12
	global_load_dword v10, v[2:3], off offset:512
	v_add_u32_e32 v2, s7, v11
	v_ashrrev_i32_e32 v3, 31, v2
	v_lshlrev_b64 v[2:3], 12, v[2:3]
	v_lshl_add_u64 v[2:3], v[0:1], 0, v[2:3]
	v_lshl_add_u64 v[2:3], v[2:3], 0, s[96:97]
	v_lshl_add_u64 v[2:3], v[2:3], 0, v[166:167]
	global_load_dword v12, v[2:3], off offset:512
	v_add_u32_e32 v2, 0x800, v4
	v_ashrrev_i32_e32 v13, 5, v2
	v_add_u32_e32 v2, s7, v13
	v_ashrrev_i32_e32 v3, 31, v2
	v_lshlrev_b64 v[2:3], 12, v[2:3]
	v_lshl_add_u64 v[2:3], v[0:1], 0, v[2:3]
	v_lshl_add_u64 v[2:3], v[2:3], 0, s[96:97]
	v_lshl_add_u64 v[2:3], v[2:3], 0, v[166:167]
	global_load_dword v14, v[2:3], off offset:512
	v_add_u32_e32 v2, 0xa00, v4
	v_ashrrev_i32_e32 v15, 5, v2
	v_add_u32_e32 v2, s7, v15
	v_ashrrev_i32_e32 v3, 31, v2
	v_lshlrev_b64 v[2:3], 12, v[2:3]
	v_lshl_add_u64 v[2:3], v[0:1], 0, v[2:3]
	v_lshl_add_u64 v[2:3], v[2:3], 0, s[96:97]
	v_lshl_add_u64 v[2:3], v[2:3], 0, v[166:167]
	global_load_dword v16, v[2:3], off offset:512
	v_add_u32_e32 v2, 0xc00, v4
	v_ashrrev_i32_e32 v17, 5, v2
	v_add_u32_e32 v2, s7, v17
	v_ashrrev_i32_e32 v3, 31, v2
	v_lshlrev_b64 v[2:3], 12, v[2:3]
	v_lshl_add_u64 v[2:3], v[0:1], 0, v[2:3]
	v_lshl_add_u64 v[2:3], v[2:3], 0, s[96:97]
	v_lshl_add_u64 v[2:3], v[2:3], 0, v[166:167]
	global_load_dword v18, v[2:3], off offset:512
	v_add_u32_e32 v2, 0xe00, v4
	v_ashrrev_i32_e32 v19, 5, v2
	v_add_u32_e32 v2, s7, v19
	v_ashrrev_i32_e32 v3, 31, v2
	v_lshlrev_b64 v[2:3], 12, v[2:3]
	v_lshl_add_u64 v[2:3], v[0:1], 0, v[2:3]
	v_lshl_add_u64 v[2:3], v[2:3], 0, s[96:97]
	v_lshl_add_u64 v[2:3], v[2:3], 0, v[166:167]
	global_load_dword v20, v[2:3], off offset:512
	v_add_u32_e32 v2, 0x1000, v4
	v_ashrrev_i32_e32 v21, 5, v2
	v_add_u32_e32 v2, s7, v21
	v_ashrrev_i32_e32 v3, 31, v2
	v_lshlrev_b64 v[2:3], 12, v[2:3]
	v_lshl_add_u64 v[2:3], v[0:1], 0, v[2:3]
	v_lshl_add_u64 v[2:3], v[2:3], 0, s[96:97]
	v_lshl_add_u64 v[2:3], v[2:3], 0, v[166:167]
	global_load_dword v22, v[2:3], off offset:512
	v_add_u32_e32 v2, 0x1200, v4
	v_ashrrev_i32_e32 v23, 5, v2
	v_add_u32_e32 v2, s7, v23
	v_ashrrev_i32_e32 v3, 31, v2
	v_lshlrev_b64 v[2:3], 12, v[2:3]
	v_lshl_add_u64 v[2:3], v[0:1], 0, v[2:3]
	v_lshl_add_u64 v[2:3], v[2:3], 0, s[96:97]
	v_lshl_add_u64 v[2:3], v[2:3], 0, v[166:167]
	global_load_dword v24, v[2:3], off offset:512
	v_add_u32_e32 v2, 0x1400, v4
	v_ashrrev_i32_e32 v25, 5, v2
	v_add_u32_e32 v2, s7, v25
	v_ashrrev_i32_e32 v3, 31, v2
	v_lshlrev_b64 v[2:3], 12, v[2:3]
	v_lshl_add_u64 v[2:3], v[0:1], 0, v[2:3]
	v_lshl_add_u64 v[2:3], v[2:3], 0, s[96:97]
	v_lshl_add_u64 v[2:3], v[2:3], 0, v[166:167]
	global_load_dword v26, v[2:3], off offset:512
	v_add_u32_e32 v2, 0x1600, v4
	v_ashrrev_i32_e32 v27, 5, v2
	v_add_u32_e32 v2, s7, v27
	v_ashrrev_i32_e32 v3, 31, v2
	v_lshlrev_b64 v[2:3], 12, v[2:3]
	v_lshl_add_u64 v[2:3], v[0:1], 0, v[2:3]
	v_lshl_add_u64 v[2:3], v[2:3], 0, s[96:97]
	v_lshl_add_u64 v[2:3], v[2:3], 0, v[166:167]
	global_load_dword v28, v[2:3], off offset:512
	v_add_u32_e32 v2, 0x1800, v4
	v_ashrrev_i32_e32 v29, 5, v2
	v_add_u32_e32 v2, s7, v29
	v_ashrrev_i32_e32 v3, 31, v2
	v_lshlrev_b64 v[2:3], 12, v[2:3]
	v_lshl_add_u64 v[2:3], v[0:1], 0, v[2:3]
	v_lshl_add_u64 v[2:3], v[2:3], 0, s[96:97]
	v_lshl_add_u64 v[2:3], v[2:3], 0, v[166:167]
	global_load_dword v30, v[2:3], off offset:512
	v_add_u32_e32 v2, 0x1a00, v4
	v_ashrrev_i32_e32 v31, 5, v2
	v_add_u32_e32 v2, s7, v31
	v_ashrrev_i32_e32 v3, 31, v2
	v_lshlrev_b64 v[2:3], 12, v[2:3]
	v_lshl_add_u64 v[2:3], v[0:1], 0, v[2:3]
	v_lshl_add_u64 v[2:3], v[2:3], 0, s[96:97]
	v_lshl_add_u64 v[2:3], v[2:3], 0, v[166:167]
	global_load_dword v32, v[2:3], off offset:512
	v_add_u32_e32 v2, 0x1c00, v4
	v_ashrrev_i32_e32 v33, 5, v2
	v_add_u32_e32 v2, s7, v33
	v_ashrrev_i32_e32 v3, 31, v2
	v_lshlrev_b64 v[2:3], 12, v[2:3]
	v_lshl_add_u64 v[2:3], v[0:1], 0, v[2:3]
	v_lshl_add_u64 v[2:3], v[2:3], 0, s[96:97]
	v_lshl_add_u64 v[2:3], v[2:3], 0, v[166:167]
	global_load_dword v34, v[2:3], off offset:512
	v_add_u32_e32 v2, 0x1e00, v4
	v_ashrrev_i32_e32 v35, 5, v2
	v_add_u32_e32 v2, s7, v35
	v_ashrrev_i32_e32 v3, 31, v2
	v_lshlrev_b64 v[2:3], 12, v[2:3]
	v_lshl_add_u64 v[0:1], v[0:1], 0, v[2:3]
	v_lshl_add_u64 v[0:1], v[0:1], 0, s[96:97]
	v_lshl_add_u64 v[0:1], v[0:1], 0, v[166:167]
	global_load_dword v36, v[0:1], off offset:512
	v_lshl_add_u32 v0, v88, 2, s92
	v_mad_u64_u32 v[2:3], s[10:11], v5, s93, v[0:1]
	s_waitcnt vmcnt(15)
	ds_write_b32 v2, v6
	v_mad_u64_u32 v[2:3], s[10:11], v7, s93, v[0:1]
	s_waitcnt vmcnt(14)
	ds_write_b32 v2, v8
	v_mad_u64_u32 v[2:3], s[10:11], v9, s93, v[0:1]
	s_waitcnt vmcnt(13)
	ds_write_b32 v2, v10
	v_mad_u64_u32 v[2:3], s[10:11], v11, s93, v[0:1]
	s_waitcnt vmcnt(12)
	ds_write_b32 v2, v12
	v_mad_u64_u32 v[2:3], s[10:11], v13, s93, v[0:1]
	s_waitcnt vmcnt(11)
	ds_write_b32 v2, v14
	v_mad_u64_u32 v[2:3], s[10:11], v15, s93, v[0:1]
	s_waitcnt vmcnt(10)
	ds_write_b32 v2, v16
	v_mad_u64_u32 v[2:3], s[10:11], v17, s93, v[0:1]
	s_waitcnt vmcnt(9)
	ds_write_b32 v2, v18
	v_mad_u64_u32 v[2:3], s[10:11], v19, s93, v[0:1]
	s_waitcnt vmcnt(8)
	ds_write_b32 v2, v20
	v_mad_u64_u32 v[2:3], s[10:11], v21, s93, v[0:1]
	s_waitcnt vmcnt(7)
	ds_write_b32 v2, v22
	v_mad_u64_u32 v[2:3], s[10:11], v23, s93, v[0:1]
	s_waitcnt vmcnt(6)
	ds_write_b32 v2, v24
	v_mad_u64_u32 v[2:3], s[10:11], v25, s93, v[0:1]
	s_lshl_b32 s7, s5, 8
	s_waitcnt vmcnt(5)
	ds_write_b32 v2, v26
	v_mad_u64_u32 v[2:3], s[10:11], v27, s93, v[0:1]
	s_and_b32 s7, s7, 0x700
	s_or_b32 s6, s6, s7
	v_lshlrev_b32_e32 v16, 2, v37
	v_mov_b32_e32 v17, 0xff800000
	s_waitcnt vmcnt(4)
	ds_write_b32 v2, v28
	v_mad_u64_u32 v[2:3], s[10:11], v29, s93, v[0:1]
	s_waitcnt vmcnt(3)
	ds_write_b32 v2, v30
	v_mad_u64_u32 v[2:3], s[10:11], v31, s93, v[0:1]
	s_waitcnt vmcnt(2)
	ds_write_b32 v2, v32
	v_mad_u64_u32 v[2:3], s[10:11], v33, s93, v[0:1]
	v_mad_u64_u32 v[0:1], s[10:11], v35, s93, v[0:1]
	v_or_b32_e32 v1, s6, v88
	s_waitcnt vmcnt(1)
	ds_write_b32 v2, v34
	v_and_or_b32 v2, s5, 24, v37
	v_lshlrev_b32_e32 v2, 4, v2
	s_waitcnt vmcnt(0)
	ds_write_b32 v0, v36
	v_ashrrev_i32_e32 v0, 1, v4
	v_and_b32_e32 v0, 0xffffffe0, v0
	v_add_u32_e32 v86, v1, v0
	v_ashrrev_i32_e32 v87, 31, v86
	v_alignbit_b32 v0, v87, v86, 8
	v_mad_u64_u32 v[0:1], s[6:7], v0, s77, v[64:65]
	v_lshlrev_b32_e32 v3, 9, v86
	v_mad_u32_u24 v1, v87, s77, v1
	v_and_b32_e32 v166, 0x1fe00, v3
	v_lshl_add_u64 v[0:1], v[0:1], 0, v[166:167]
	s_mov_b64 s[6:7], 0x74c2800
	v_mov_b32_e32 v3, v167
	v_lshl_add_u64 v[0:1], v[0:1], 0, s[6:7]
	v_lshl_add_u64 v[2:3], v[0:1], 0, v[2:3]
	s_mov_b64 s[6:7], 0x360000
	v_lshl_add_u64 v[6:7], v[2:3], 0, s[6:7]
	s_mov_b32 s6, 0x360000
	v_add_co_u32_e32 v2, vcc, s6, v2
	s_mov_b64 s[6:7], 0x380000
	s_nop 0
	v_addc_co_u32_e32 v3, vcc, 0, v3, vcc
	global_load_dwordx4 v[48:51], v[2:3], off
	global_load_dwordx4 v[52:55], v[6:7], off offset:32
	global_load_dwordx4 v[56:59], v[6:7], off offset:64
	global_load_dwordx4 v[60:63], v[6:7], off offset:96
	v_or_b32_e32 v2, s8, v16
	v_lshlrev_b32_e32 v166, 1, v2
	v_lshl_add_u64 v[0:1], v[0:1], 0, v[166:167]
	v_lshl_add_u64 v[2:3], v[0:1], 0, s[6:7]
	s_mov_b32 s6, 0x380000
	v_add_co_u32_e32 v0, vcc, s6, v0
	s_mov_b64 s[6:7], -1
	s_nop 0
	v_addc_co_u32_e32 v1, vcc, 0, v1, vcc
	global_load_dwordx2 v[84:85], v[0:1], off
	global_load_dwordx2 v[78:79], v[2:3], off offset:16
	global_load_dwordx2 v[76:77], v[2:3], off offset:32
	global_load_dwordx2 v[74:75], v[2:3], off offset:48
	global_load_dwordx2 v[72:73], v[2:3], off offset:64
	global_load_dwordx2 v[70:71], v[2:3], off offset:80
	global_load_dwordx2 v[68:69], v[2:3], off offset:96
	global_load_dwordx2 v[66:67], v[2:3], off offset:112
	v_and_b32_e32 v0, 0xff, v4
	v_ashrrev_i32_e32 v2, 4, v4
	v_and_b32_e32 v3, -16, v2
	v_mad_u32_u24 v4, v0, s93, v38
	v_lshl_add_u32 v7, v3, 2, v4
	s_waitcnt lgkmcnt(0)
	s_barrier
	v_lshlrev_b32_e32 v5, 1, v0
	ds_read2_b32 v[0:1], v7 offset1:1
	v_add_u32_e32 v6, 0, v5
	v_mul_lo_u32 v3, v3, s69
	v_add_u32_e32 v8, v6, v3
	v_add3_u32 v3, 0, v3, v5
	s_waitcnt lgkmcnt(0)
	ds_write_b16 v8, v0 offset:36864
	ds_write_b16_d16_hi v3, v0 offset:37384
	ds_write_b16 v3, v1 offset:37904
	ds_write_b16_d16_hi v3, v1 offset:38424
	ds_read2_b32 v[0:1], v7 offset0:2 offset1:3
	s_waitcnt lgkmcnt(0)
	ds_write_b16 v3, v0 offset:38944
	ds_write_b16_d16_hi v3, v0 offset:39464
	ds_write_b16 v3, v1 offset:39984
	ds_write_b16_d16_hi v3, v1 offset:40504
	ds_read2_b32 v[0:1], v7 offset0:4 offset1:5
	s_waitcnt lgkmcnt(0)
	ds_write_b16 v3, v0 offset:41024
	ds_write_b16_d16_hi v3, v0 offset:41544
	ds_write_b16 v3, v1 offset:42064
	ds_write_b16_d16_hi v3, v1 offset:42584
	ds_read2_b32 v[0:1], v7 offset0:6 offset1:7
	s_waitcnt lgkmcnt(0)
	ds_write_b16 v3, v0 offset:43104
	ds_write_b16_d16_hi v3, v0 offset:43624
	ds_write_b16 v3, v1 offset:44144
	ds_write_b16_d16_hi v3, v1 offset:44664
	ds_read2_b32 v[0:1], v7 offset0:8 offset1:9
	s_waitcnt lgkmcnt(0)
	ds_write_b16 v3, v0 offset:45184
	ds_write_b16_d16_hi v3, v0 offset:45704
	ds_write_b16 v3, v1 offset:46224
	ds_write_b16_d16_hi v3, v1 offset:46744
	ds_read2_b32 v[0:1], v7 offset0:10 offset1:11
	s_waitcnt lgkmcnt(0)
	ds_write_b16 v3, v0 offset:47264
	ds_write_b16_d16_hi v3, v0 offset:47784
	ds_write_b16 v3, v1 offset:48304
	ds_write_b16_d16_hi v3, v1 offset:48824
	ds_read2_b32 v[0:1], v7 offset0:12 offset1:13
	s_waitcnt lgkmcnt(0)
	ds_write_b16 v3, v0 offset:49344
	ds_write_b16_d16_hi v3, v0 offset:49864
	ds_write_b16 v3, v1 offset:50384
	ds_write_b16_d16_hi v3, v1 offset:50904
	ds_read_b32 v0, v7 offset:56
	s_waitcnt lgkmcnt(0)
	ds_write_b16 v3, v0 offset:51424
	ds_write_b16_d16_hi v3, v0 offset:51944
	v_or_b32_e32 v0, 15, v2
	v_lshl_add_u32 v1, v0, 2, v4
	ds_read_b32 v1, v1
	v_mul_lo_u32 v0, v0, s69
	v_add_u32_e32 v2, v6, v0
	v_add3_u32 v0, 0, v0, v5
	s_waitcnt lgkmcnt(0)
	ds_write_b16 v2, v1 offset:36864
	ds_write_b16_d16_hi v0, v1 offset:37384
	s_waitcnt lgkmcnt(0)
	s_barrier
